# v15 plus P3 mid-hook gate loads issued at the end of the preceding K-loop trip (before its trailing barrier) so the two wave halves' hook latencies overlap
# speedup vs baseline: 1.0107x; 1.0098x over previous
; #define PG8_STAGE(bufoff, gbase, voff) do { _Pragma("unroll") for (int _i = 0; _i < 2; ++_i) \
;         __builtin_amdgcn_global_load_lds((const unsigned*)((const char*)(gbase) + (voff)[_i]), (PG8_LAS unsigned*)(lds + (bufoff) + ldsw + _i * 8192), 16, 0, 0); } while (0)
; #define PG8_LDA(dst, b, h) do { _Pragma("unroll") for (int m = 0; m < 4; ++m) _Pragma("unroll") for (int k = 0; k < 2; ++k) dst[m][k] = *(const PG8_LAS bf16x8*)(lds + PG8_SA(b, h) + aoff + m * 2048 + k * 1024); } while (0)
; #define PG8_LDB(dst, b, h) do { _Pragma("unroll") for (int n = 0; n < 2; ++n) _Pragma("unroll") for (int k = 0; k < 2; ++k) dst[n][k] = *(const PG8_LAS bf16x8*)(lds + PG8_SB(b, h) + boff + n * 2048 + k * 1024); } while (0)
; #define PG8_MMA(ai, bj, At, Bt) do { __builtin_amdgcn_s_setprio(1); _Pragma("unroll") for (int m = 0; m < 4; ++m) _Pragma("unroll") for (int n = 0; n < 2; ++n) _Pragma("unroll") for (int k = 0; k < 2; ++k) \
;         acc[ai][bj][m][n] = __builtin_amdgcn_mfma_f32_16x16x32_bf16(Bt[n][k], At[m][k], acc[ai][bj][m][n], 0, 0, 0); __builtin_amdgcn_s_setprio(0); } while (0)
; #define PG8_WAIT_V(n) asm volatile("s_waitcnt vmcnt(" #n ")" ::: "memory")
; template <class Epi, class Sched, bool ALIGN_EPI = false, bool SP2 = false>
; __device__ __forceinline__ void gemm_phase(PG8_LAS unsigned char* lds, const Gemm g, const Sched& S, const Epi& E, const int wave_s) {
;     ...
;             const bool last = (t == nt - 2);
;             if constexpr (Epi::HAS_PRE) { if (last) E.pre(cur, wr, fr, pf); }
;             const char* a1 = cA + (size_t)(t + 1) * kstep;
;             const char* a2 = last ? nA : cA + (size_t)(t + 2) * kstep; const char* b2 = last ? nB : cB + (size_t)(t + 2) * kstep;
;             const char* a3 = a2 + kstep; const char* b3 = b2 + kstep;
;             if (last && has_next) S.a_ready(nxt);
;             if constexpr (SP2) {
;             PG8_LDB(B0, 0, 0); PG8_LDB(B1, 0, 1); PG8_SCHED; PG8_LDA(At, 0, 0); PG8_STAGE(PG8_SA(1, 1), a1 + hA, voffA);
;             PG8_WAIT_V(8); PG8_WAIT_L(0); PG8_BAR; PG8_MMA(0, 0, At, B0); PG8_MMA(0, 1, At, B1); PG8_BAR; PG8_SCHED;
;             PG8_LDA(At, 0, 1); PG8_STAGE(PG8_SB(0, 0), b2, voffB); PG8_STAGE(PG8_SB(0, 1), b2 + hB, voffB); PG8_STAGE(PG8_SA(0, 0), a2, voffA);
;             PG8_WAIT_V(8); PG8_WAIT_L(0); PG8_BAR; PG8_MMA(1, 0, At, B0); PG8_MMA(1, 1, At, B1); PG8_BAR; PG8_SCHED;
.LBB0_622:
	s_add_u32 s8, s64, s66
	s_addc_u32 s9, s65, s67
	s_add_u32 s8, s8, 0x100
	s_addc_u32 s9, s9, 0
	s_add_u32 s68, s92, s66
	s_addc_u32 s69, s93, s67
	s_add_i32 s95, 0, 0x10000
	v_add_u32_e32 v164, s95, v154
	v_add_u32_e32 v180, s89, v154
	ds_read_b128 v[128:131], v164
	ds_read_b128 v[156:159], v164 offset:1024
	ds_read_b128 v[160:163], v164 offset:2048
	ds_read_b128 v[164:167], v164 offset:3072
	ds_read_b128 v[168:171], v180
	ds_read_b128 v[172:175], v180 offset:1024
	ds_read_b128 v[176:179], v180 offset:2048
	ds_read_b128 v[180:183], v180 offset:3072
	s_cmpk_eq_i32 s66, 0x700
	s_cselect_b32 s71, s34, s9
	s_cselect_b32 s70, s35, s8
	s_cselect_b32 s69, s90, s69
	s_cselect_b32 s68, s91, s68
	v_lshl_add_u64 v[212:213], v[148:149], 0, s[66:67]
	s_add_i32 m0, s75, 0xc000
	ds_read_b128 v[184:187], v155
	ds_read_b128 v[188:191], v155 offset:1024
	ds_read_b128 v[192:195], v155 offset:2048
	ds_read_b128 v[196:199], v155 offset:3072
	ds_read_b128 v[200:203], v155 offset:4096
	ds_read_b128 v[204:207], v155 offset:5120
	ds_read_b128 v[208:211], v155 offset:6144
	ds_read_b128 v[218:221], v155 offset:7168
	global_load_lds_dwordx4 v[212:213], off
	v_lshl_add_u64 v[212:213], v[150:151], 0, s[66:67]
	s_add_i32 m0, s75, 0xe000
	s_nop 0
	global_load_lds_dwordx4 v[212:213], off
	s_waitcnt vmcnt(8)
	s_waitcnt lgkmcnt(0)
	s_barrier
	s_setprio 1
	s_waitcnt lgkmcnt(0)
	v_mfma_f32_16x16x32_bf16 v[124:127], v[128:131], v[184:187], v[124:127]
	v_mfma_f32_16x16x32_bf16 v[120:123], v[160:163], v[184:187], v[120:123]
	v_mfma_f32_16x16x32_bf16 v[108:111], v[128:131], v[192:195], v[108:111]
	v_mfma_f32_16x16x32_bf16 v[104:107], v[160:163], v[192:195], v[104:107]
	v_mfma_f32_16x16x32_bf16 v[92:95], v[128:131], v[200:203], v[92:95]
	v_mfma_f32_16x16x32_bf16 v[88:91], v[160:163], v[200:203], v[88:91]
	v_mfma_f32_16x16x32_bf16 v[76:79], v[128:131], v[208:211], v[76:79]
	v_mfma_f32_16x16x32_bf16 v[72:75], v[160:163], v[208:211], v[72:75]
	v_mfma_f32_16x16x32_bf16 v[124:127], v[156:159], v[188:191], v[124:127]
	v_mfma_f32_16x16x32_bf16 v[120:123], v[164:167], v[188:191], v[120:123]
	v_mfma_f32_16x16x32_bf16 v[108:111], v[156:159], v[196:199], v[108:111]
	v_mfma_f32_16x16x32_bf16 v[104:107], v[164:167], v[196:199], v[104:107]
	v_mfma_f32_16x16x32_bf16 v[92:95], v[156:159], v[204:207], v[92:95]
	v_mfma_f32_16x16x32_bf16 v[88:91], v[164:167], v[204:207], v[88:91]
	v_mfma_f32_16x16x32_bf16 v[76:79], v[156:159], v[218:221], v[76:79]
	v_mfma_f32_16x16x32_bf16 v[72:75], v[164:167], v[218:221], v[72:75]
	s_setprio 0
	s_setprio 1
	v_mfma_f32_16x16x32_bf16 v[116:119], v[168:171], v[184:187], v[116:119]
	v_mfma_f32_16x16x32_bf16 v[112:115], v[176:179], v[184:187], v[112:115]
	v_mfma_f32_16x16x32_bf16 v[100:103], v[168:171], v[192:195], v[100:103]
	v_mfma_f32_16x16x32_bf16 v[96:99], v[176:179], v[192:195], v[96:99]
	v_mfma_f32_16x16x32_bf16 v[84:87], v[168:171], v[200:203], v[84:87]
	v_mfma_f32_16x16x32_bf16 v[80:83], v[176:179], v[200:203], v[80:83]
	v_mfma_f32_16x16x32_bf16 v[68:71], v[168:171], v[208:211], v[68:71]
	v_mfma_f32_16x16x32_bf16 v[64:67], v[176:179], v[208:211], v[64:67]
	v_mfma_f32_16x16x32_bf16 v[116:119], v[172:175], v[188:191], v[116:119]
	v_mfma_f32_16x16x32_bf16 v[112:115], v[180:183], v[188:191], v[112:115]
	v_mfma_f32_16x16x32_bf16 v[100:103], v[172:175], v[196:199], v[100:103]
	v_mfma_f32_16x16x32_bf16 v[96:99], v[180:183], v[196:199], v[96:99]
	v_mfma_f32_16x16x32_bf16 v[84:87], v[172:175], v[204:207], v[84:87]
	v_mfma_f32_16x16x32_bf16 v[80:83], v[180:183], v[204:207], v[80:83]
	v_mfma_f32_16x16x32_bf16 v[68:71], v[172:175], v[218:221], v[68:71]
	v_mfma_f32_16x16x32_bf16 v[64:67], v[180:183], v[218:221], v[64:67]
	s_setprio 0
	s_barrier
	s_add_i32 s8, s95, s72
	v_lshl_add_u64 v[212:213], s[68:69], 0, v[136:137]
	s_mov_b32 m0, s8
	ds_read_b128 v[184:187], v155 offset:16384
	ds_read_b128 v[188:191], v155 offset:17408
	ds_read_b128 v[192:195], v155 offset:18432
	ds_read_b128 v[196:199], v155 offset:19456
	ds_read_b128 v[200:203], v155 offset:20480
	ds_read_b128 v[204:207], v155 offset:21504
	ds_read_b128 v[208:211], v155 offset:22528
	ds_read_b128 v[218:221], v155 offset:23552
	global_load_lds_dwordx4 v[212:213], off
	s_add_i32 m0, s8, 0x2000
	s_add_u32 s8, s68, 0x40000
	v_lshl_add_u64 v[222:223], s[68:69], 0, v[132:133]
	s_addc_u32 s9, s69, 0
	s_add_i32 s95, s89, s72
	global_load_lds_dwordx4 v[222:223], off
	v_lshl_add_u64 v[224:225], s[8:9], 0, v[136:137]
	s_mov_b32 m0, s95
	v_lshl_add_u64 v[226:227], s[70:71], 0, v[134:135]
	global_load_lds_dwordx4 v[224:225], off
	v_lshl_add_u64 v[224:225], s[8:9], 0, v[132:133]
	s_add_i32 m0, s95, 0x2000
	s_nop 0
	global_load_lds_dwordx4 v[224:225], off
	v_lshl_add_u64 v[224:225], s[70:71], 0, v[138:139]
	s_mov_b32 m0, s75
	s_nop 0
	global_load_lds_dwordx4 v[224:225], off
	s_mov_b32 m0, s76
	s_nop 0
	global_load_lds_dwordx4 v[226:227], off
	s_waitcnt vmcnt(8)
	s_waitcnt lgkmcnt(0)
	s_barrier
; #define PG8_STAGE(bufoff, gbase, voff) do { _Pragma("unroll") for (int _i = 0; _i < 2; ++_i) \
;         __builtin_amdgcn_global_load_lds((const unsigned*)((const char*)(gbase) + (voff)[_i]), (PG8_LAS unsigned*)(lds + (bufoff) + ldsw + _i * 8192), 16, 0, 0); } while (0)
; #define PG8_LDA(dst, b, h) do { _Pragma("unroll") for (int m = 0; m < 4; ++m) _Pragma("unroll") for (int k = 0; k < 2; ++k) dst[m][k] = *(const PG8_LAS bf16x8*)(lds + PG8_SA(b, h) + aoff + m * 2048 + k * 1024); } while (0)
; #define PG8_LDB(dst, b, h) do { _Pragma("unroll") for (int n = 0; n < 2; ++n) _Pragma("unroll") for (int k = 0; k < 2; ++k) dst[n][k] = *(const PG8_LAS bf16x8*)(lds + PG8_SB(b, h) + boff + n * 2048 + k * 1024); } while (0)
; #define PG8_MMA(ai, bj, At, Bt) do { __builtin_amdgcn_s_setprio(1); _Pragma("unroll") for (int m = 0; m < 4; ++m) _Pragma("unroll") for (int n = 0; n < 2; ++n) _Pragma("unroll") for (int k = 0; k < 2; ++k) \
;         acc[ai][bj][m][n] = __builtin_amdgcn_mfma_f32_16x16x32_bf16(Bt[n][k], At[m][k], acc[ai][bj][m][n], 0, 0, 0); __builtin_amdgcn_s_setprio(0); } while (0)
; #define PG8_WAIT_V(n) asm volatile("s_waitcnt vmcnt(" #n ")" ::: "memory")
; #define PG8_WAIT_L(n) asm volatile("s_waitcnt lgkmcnt(" #n ")" ::: "memory")
; #define PG8_BAR __builtin_amdgcn_s_barrier()
; #define PG8_SCHED __builtin_amdgcn_sched_barrier(0)
; template <class Epi, class Sched, bool ALIGN_EPI = false, bool SP2 = false>
; __device__ __forceinline__ void gemm_phase(PG8_LAS unsigned char* lds, const Gemm g, const Sched& S, const Epi& E, const int wave_s) {
;     ...
;             PG8_WAIT_V(8); PG8_WAIT_L(0); PG8_BAR; PG8_MMA(1, 0, At, B0); PG8_MMA(1, 1, At, B1); PG8_BAR; PG8_SCHED;
;             PG8_LDB(B0, 1, 0); PG8_LDB(B1, 1, 1); PG8_SCHED; PG8_LDA(At, 1, 0); PG8_STAGE(PG8_SA(0, 1), a2 + hA, voffA);
;             PG8_WAIT_V(8); PG8_WAIT_L(0); PG8_BAR; PG8_MMA(0, 0, At, B0); PG8_MMA(0, 1, At, B1); PG8_BAR; PG8_SCHED;
;             PG8_LDA(At, 1, 1); PG8_STAGE(PG8_SB(1, 0), b3, voffB); PG8_STAGE(PG8_SB(1, 1), b3 + hB, voffB); PG8_STAGE(PG8_SA(1, 0), a3, voffA);
	s_setprio 1
	s_waitcnt lgkmcnt(0)
	v_mfma_f32_16x16x32_bf16 v[60:63], v[128:131], v[184:187], v[60:63]
	v_mfma_f32_16x16x32_bf16 v[56:59], v[160:163], v[184:187], v[56:59]
	v_mfma_f32_16x16x32_bf16 v[44:47], v[128:131], v[192:195], v[44:47]
	v_mfma_f32_16x16x32_bf16 v[40:43], v[160:163], v[192:195], v[40:43]
	v_mfma_f32_16x16x32_bf16 v[28:31], v[128:131], v[200:203], v[28:31]
	v_mfma_f32_16x16x32_bf16 v[24:27], v[160:163], v[200:203], v[24:27]
	v_mfma_f32_16x16x32_bf16 v[12:15], v[128:131], v[208:211], v[12:15]
	v_mfma_f32_16x16x32_bf16 v[8:11], v[160:163], v[208:211], v[8:11]
	v_mfma_f32_16x16x32_bf16 v[60:63], v[156:159], v[188:191], v[60:63]
	v_mfma_f32_16x16x32_bf16 v[56:59], v[164:167], v[188:191], v[56:59]
	v_mfma_f32_16x16x32_bf16 v[44:47], v[156:159], v[196:199], v[44:47]
	v_mfma_f32_16x16x32_bf16 v[40:43], v[164:167], v[196:199], v[40:43]
	v_mfma_f32_16x16x32_bf16 v[28:31], v[156:159], v[204:207], v[28:31]
	v_mfma_f32_16x16x32_bf16 v[24:27], v[164:167], v[204:207], v[24:27]
	v_mfma_f32_16x16x32_bf16 v[12:15], v[156:159], v[218:221], v[12:15]
	v_mfma_f32_16x16x32_bf16 v[8:11], v[164:167], v[218:221], v[8:11]
	s_setprio 0
	s_setprio 1
	v_mfma_f32_16x16x32_bf16 v[52:55], v[168:171], v[184:187], v[52:55]
	v_mfma_f32_16x16x32_bf16 v[48:51], v[176:179], v[184:187], v[48:51]
	v_mfma_f32_16x16x32_bf16 v[36:39], v[168:171], v[192:195], v[36:39]
	v_mfma_f32_16x16x32_bf16 v[32:35], v[176:179], v[192:195], v[32:35]
	v_mfma_f32_16x16x32_bf16 v[20:23], v[168:171], v[200:203], v[20:23]
	v_mfma_f32_16x16x32_bf16 v[16:19], v[176:179], v[200:203], v[16:19]
	v_mfma_f32_16x16x32_bf16 v[4:7], v[168:171], v[208:211], v[4:7]
	v_mfma_f32_16x16x32_bf16 v[0:3], v[176:179], v[208:211], v[0:3]
	v_mfma_f32_16x16x32_bf16 v[52:55], v[172:175], v[188:191], v[52:55]
	v_mfma_f32_16x16x32_bf16 v[48:51], v[180:183], v[188:191], v[48:51]
	v_mfma_f32_16x16x32_bf16 v[36:39], v[172:175], v[196:199], v[36:39]
	v_mfma_f32_16x16x32_bf16 v[32:35], v[180:183], v[196:199], v[32:35]
	v_mfma_f32_16x16x32_bf16 v[20:23], v[172:175], v[204:207], v[20:23]
	v_mfma_f32_16x16x32_bf16 v[16:19], v[180:183], v[204:207], v[16:19]
	v_mfma_f32_16x16x32_bf16 v[4:7], v[172:175], v[218:221], v[4:7]
	v_mfma_f32_16x16x32_bf16 v[0:3], v[180:183], v[218:221], v[0:3]
	s_setprio 0
	s_barrier
	s_add_i32 s95, 0, 0x18000
	s_add_i32 s96, 0, 0x1c000
	v_add_u32_e32 v164, s95, v154
	v_add_u32_e32 v180, s96, v154
	ds_read_b128 v[128:131], v164
	ds_read_b128 v[156:159], v164 offset:1024
	ds_read_b128 v[160:163], v164 offset:2048
	ds_read_b128 v[164:167], v164 offset:3072
	ds_read_b128 v[168:171], v180
	ds_read_b128 v[172:175], v180 offset:1024
	ds_read_b128 v[176:179], v180 offset:2048
	ds_read_b128 v[180:183], v180 offset:3072
	s_add_u32 s8, s70, 0x40000
	s_addc_u32 s9, s71, 0
	s_mov_b32 m0, s77
	v_lshl_add_u64 v[228:229], s[8:9], 0, v[138:139]
	ds_read_b128 v[184:187], v155 offset:32768
	ds_read_b128 v[188:191], v155 offset:33792
	ds_read_b128 v[192:195], v155 offset:34816
	ds_read_b128 v[196:199], v155 offset:35840
	ds_read_b128 v[200:203], v155 offset:36864
	ds_read_b128 v[204:207], v155 offset:37888
	ds_read_b128 v[208:211], v155 offset:38912
	ds_read_b128 v[218:221], v155 offset:39936
	global_load_lds_dwordx4 v[228:229], off
	v_lshl_add_u64 v[228:229], s[8:9], 0, v[134:135]
	s_mov_b32 m0, s78
	s_nop 0
	global_load_lds_dwordx4 v[228:229], off
	s_waitcnt vmcnt(8)
	s_waitcnt lgkmcnt(0)
	s_barrier
	s_setprio 1
	s_waitcnt lgkmcnt(0)
	v_mfma_f32_16x16x32_bf16 v[124:127], v[128:131], v[184:187], v[124:127]
	v_mfma_f32_16x16x32_bf16 v[120:123], v[160:163], v[184:187], v[120:123]
	v_mfma_f32_16x16x32_bf16 v[108:111], v[128:131], v[192:195], v[108:111]
	v_mfma_f32_16x16x32_bf16 v[104:107], v[160:163], v[192:195], v[104:107]
	v_mfma_f32_16x16x32_bf16 v[92:95], v[128:131], v[200:203], v[92:95]
	v_mfma_f32_16x16x32_bf16 v[88:91], v[160:163], v[200:203], v[88:91]
	v_mfma_f32_16x16x32_bf16 v[76:79], v[128:131], v[208:211], v[76:79]
	v_mfma_f32_16x16x32_bf16 v[72:75], v[160:163], v[208:211], v[72:75]
	v_mfma_f32_16x16x32_bf16 v[124:127], v[156:159], v[188:191], v[124:127]
	v_mfma_f32_16x16x32_bf16 v[120:123], v[164:167], v[188:191], v[120:123]
	v_mfma_f32_16x16x32_bf16 v[108:111], v[156:159], v[196:199], v[108:111]
	v_mfma_f32_16x16x32_bf16 v[104:107], v[164:167], v[196:199], v[104:107]
	v_mfma_f32_16x16x32_bf16 v[92:95], v[156:159], v[204:207], v[92:95]
	v_mfma_f32_16x16x32_bf16 v[88:91], v[164:167], v[204:207], v[88:91]
	v_mfma_f32_16x16x32_bf16 v[76:79], v[156:159], v[218:221], v[76:79]
	v_mfma_f32_16x16x32_bf16 v[72:75], v[164:167], v[218:221], v[72:75]
	s_setprio 0
	s_setprio 1
	v_mfma_f32_16x16x32_bf16 v[116:119], v[168:171], v[184:187], v[116:119]
	v_mfma_f32_16x16x32_bf16 v[112:115], v[176:179], v[184:187], v[112:115]
	v_mfma_f32_16x16x32_bf16 v[100:103], v[168:171], v[192:195], v[100:103]
	v_mfma_f32_16x16x32_bf16 v[96:99], v[176:179], v[192:195], v[96:99]
	v_mfma_f32_16x16x32_bf16 v[84:87], v[168:171], v[200:203], v[84:87]
	v_mfma_f32_16x16x32_bf16 v[80:83], v[176:179], v[200:203], v[80:83]
	v_mfma_f32_16x16x32_bf16 v[68:71], v[168:171], v[208:211], v[68:71]
	v_mfma_f32_16x16x32_bf16 v[64:67], v[176:179], v[208:211], v[64:67]
	v_mfma_f32_16x16x32_bf16 v[116:119], v[172:175], v[188:191], v[116:119]
	v_mfma_f32_16x16x32_bf16 v[112:115], v[180:183], v[188:191], v[112:115]
	v_mfma_f32_16x16x32_bf16 v[100:103], v[172:175], v[196:199], v[100:103]
	v_mfma_f32_16x16x32_bf16 v[96:99], v[180:183], v[196:199], v[96:99]
	v_mfma_f32_16x16x32_bf16 v[84:87], v[172:175], v[204:207], v[84:87]
	v_mfma_f32_16x16x32_bf16 v[80:83], v[180:183], v[204:207], v[80:83]
	v_mfma_f32_16x16x32_bf16 v[68:71], v[172:175], v[218:221], v[68:71]
	v_mfma_f32_16x16x32_bf16 v[64:67], v[180:183], v[218:221], v[64:67]
	s_setprio 0
	s_barrier
; __device__ __forceinline__ float bflo(unsigned w) { return __uint_as_float(w << 16); }
; __device__ __forceinline__ float bfhi(unsigned w) { return __uint_as_float(w & 0xffff0000u); }
; #define PG8_STAGE(bufoff, gbase, voff) do { _Pragma("unroll") for (int _i = 0; _i < 2; ++_i) \
;         __builtin_amdgcn_global_load_lds((const unsigned*)((const char*)(gbase) + (voff)[_i]), (PG8_LAS unsigned*)(lds + (bufoff) + ldsw + _i * 8192), 16, 0, 0); } while (0)
; #define PG8_LDA(dst, b, h) do { _Pragma("unroll") for (int m = 0; m < 4; ++m) _Pragma("unroll") for (int k = 0; k < 2; ++k) dst[m][k] = *(const PG8_LAS bf16x8*)(lds + PG8_SA(b, h) + aoff + m * 2048 + k * 1024); } while (0)
; #define PG8_MMA(ai, bj, At, Bt) do { __builtin_amdgcn_s_setprio(1); _Pragma("unroll") for (int m = 0; m < 4; ++m) _Pragma("unroll") for (int n = 0; n < 2; ++n) _Pragma("unroll") for (int k = 0; k < 2; ++k) \
;         acc[ai][bj][m][n] = __builtin_amdgcn_mfma_f32_16x16x32_bf16(Bt[n][k], At[m][k], acc[ai][bj][m][n], 0, 0, 0); __builtin_amdgcn_s_setprio(0); } while (0)
; #define PG8_WAIT_V(n) asm volatile("s_waitcnt vmcnt(" #n ")" ::: "memory")
; #define PG8_BAR __builtin_amdgcn_s_barrier()
;     __device__ __forceinline__ void scale(f32x4 (&acc)[2][2][4][2], const Unit& u, int wr, int wc, int fr, int fq, int goff) const {
;     ...
;             for (int m = 0; m < 4; ++m) { const size_t row = (size_t)(row0 + ai * HALF + m * 16);
; #pragma unroll
;                 for (int bj = 0; bj < 2; ++bj) { const u32x4 g = __builtin_nontemporal_load((const u32x4*)(G + row * 2048 + goff + col0 + bj * HALF));
;                     f32x4& v0 = acc[ai][bj][m][0]; f32x4& v1 = acc[ai][bj][m][1];
;                     v0[0] *= bflo(g.x); v0[1] *= bfhi(g.x); v0[2] *= bflo(g.y); v0[3] *= bfhi(g.y); v1[0] *= bflo(g.z); v1[1] *= bfhi(g.z); v1[2] *= bflo(g.w); v1[3] *= bfhi(g.w); }
;                 if (m & 1) asm volatile("" ::: "memory"); }
; template <class Epi, class Sched, bool ALIGN_EPI = false, bool SP2 = false>
; __device__ __forceinline__ void gemm_phase(PG8_LAS unsigned char* lds, const Gemm g, const Sched& S, const Epi& E, const int wave_s) {
;     ...
;             PG8_LDA(At, 1, 1); PG8_STAGE(PG8_SB(1, 0), b3, voffB); PG8_STAGE(PG8_SB(1, 1), b3 + hB, voffB); PG8_STAGE(PG8_SA(1, 0), a3, voffA);
;             PG8_WAIT_V(8); PG8_WAIT_L(0); PG8_BAR; PG8_MMA(1, 0, At, B0); PG8_MMA(1, 1, At, B1); PG8_BAR; PG8_SCHED;
	s_add_i32 s8, s95, s72
	v_lshl_add_u64 v[212:213], v[212:213], 0, s[6:7]
	s_mov_b32 m0, s8
	ds_read_b128 v[184:187], v155 offset:49152
	ds_read_b128 v[188:191], v155 offset:50176
	ds_read_b128 v[192:195], v155 offset:51200
	ds_read_b128 v[196:199], v155 offset:52224
	ds_read_b128 v[200:203], v155 offset:53248
	ds_read_b128 v[204:207], v155 offset:54272
	ds_read_b128 v[208:211], v155 offset:55296
	ds_read_b128 v[218:221], v155 offset:56320
	global_load_lds_dwordx4 v[212:213], off
	s_add_i32 m0, s8, 0x2000
	s_add_u32 s8, s68, 0x40080
	v_lshl_add_u64 v[212:213], v[222:223], 0, s[6:7]
	s_addc_u32 s9, s69, 0
	s_add_i32 s68, s96, s72
	global_load_lds_dwordx4 v[212:213], off
	v_lshl_add_u64 v[212:213], s[8:9], 0, v[136:137]
	s_mov_b32 m0, s68
	s_nop 0
	global_load_lds_dwordx4 v[212:213], off
	v_lshl_add_u64 v[212:213], s[8:9], 0, v[132:133]
	s_add_i32 m0, s68, 0x2000
	s_nop 0
	global_load_lds_dwordx4 v[212:213], off
	v_lshl_add_u64 v[212:213], v[224:225], 0, s[6:7]
	s_mov_b32 m0, s81
	s_nop 0
	global_load_lds_dwordx4 v[212:213], off
	v_lshl_add_u64 v[212:213], v[226:227], 0, s[6:7]
	s_mov_b32 m0, s82
	s_nop 0
	global_load_lds_dwordx4 v[212:213], off
	s_waitcnt vmcnt(8)
	s_waitcnt lgkmcnt(0)
	s_barrier
	s_setprio 1
	s_waitcnt lgkmcnt(0)
	v_mfma_f32_16x16x32_bf16 v[60:63], v[128:131], v[184:187], v[60:63]
	v_mfma_f32_16x16x32_bf16 v[56:59], v[160:163], v[184:187], v[56:59]
	v_mfma_f32_16x16x32_bf16 v[44:47], v[128:131], v[192:195], v[44:47]
	v_mfma_f32_16x16x32_bf16 v[40:43], v[160:163], v[192:195], v[40:43]
	v_mfma_f32_16x16x32_bf16 v[28:31], v[128:131], v[200:203], v[28:31]
	v_mfma_f32_16x16x32_bf16 v[24:27], v[160:163], v[200:203], v[24:27]
	v_mfma_f32_16x16x32_bf16 v[12:15], v[128:131], v[208:211], v[12:15]
	v_mfma_f32_16x16x32_bf16 v[8:11], v[160:163], v[208:211], v[8:11]
	v_mfma_f32_16x16x32_bf16 v[60:63], v[156:159], v[188:191], v[60:63]
	v_mfma_f32_16x16x32_bf16 v[56:59], v[164:167], v[188:191], v[56:59]
	v_mfma_f32_16x16x32_bf16 v[44:47], v[156:159], v[196:199], v[44:47]
	v_mfma_f32_16x16x32_bf16 v[40:43], v[164:167], v[196:199], v[40:43]
	v_mfma_f32_16x16x32_bf16 v[28:31], v[156:159], v[204:207], v[28:31]
	v_mfma_f32_16x16x32_bf16 v[24:27], v[164:167], v[204:207], v[24:27]
	v_mfma_f32_16x16x32_bf16 v[12:15], v[156:159], v[218:221], v[12:15]
	v_mfma_f32_16x16x32_bf16 v[8:11], v[164:167], v[218:221], v[8:11]
	s_setprio 0
	s_setprio 1
	v_mfma_f32_16x16x32_bf16 v[52:55], v[168:171], v[184:187], v[52:55]
	v_mfma_f32_16x16x32_bf16 v[48:51], v[176:179], v[184:187], v[48:51]
	v_mfma_f32_16x16x32_bf16 v[36:39], v[168:171], v[192:195], v[36:39]
	v_mfma_f32_16x16x32_bf16 v[32:35], v[176:179], v[192:195], v[32:35]
	v_mfma_f32_16x16x32_bf16 v[20:23], v[168:171], v[200:203], v[20:23]
	v_mfma_f32_16x16x32_bf16 v[16:19], v[176:179], v[200:203], v[16:19]
	v_mfma_f32_16x16x32_bf16 v[4:7], v[168:171], v[208:211], v[4:7]
	v_mfma_f32_16x16x32_bf16 v[0:3], v[176:179], v[208:211], v[0:3]
	v_mfma_f32_16x16x32_bf16 v[52:55], v[172:175], v[188:191], v[52:55]
	v_mfma_f32_16x16x32_bf16 v[48:51], v[180:183], v[188:191], v[48:51]
	v_mfma_f32_16x16x32_bf16 v[36:39], v[172:175], v[196:199], v[36:39]
	v_mfma_f32_16x16x32_bf16 v[32:35], v[180:183], v[196:199], v[32:35]
	v_mfma_f32_16x16x32_bf16 v[20:23], v[172:175], v[204:207], v[20:23]
	v_mfma_f32_16x16x32_bf16 v[16:19], v[180:183], v[204:207], v[16:19]
	v_mfma_f32_16x16x32_bf16 v[4:7], v[172:175], v[218:221], v[4:7]
	v_mfma_f32_16x16x32_bf16 v[0:3], v[180:183], v[218:221], v[0:3]
	s_setprio 0
	s_cmpk_lg_i32 s66, 0x300
	s_cbranch_scc1 .Lmid_early_skip
	v_mov_b32_e32 v129, v152
	v_mov_b32_e32 v128, v153
	v_add_u32_e32 v130, s51, v129
	v_ashrrev_i32_e32 v131, 31, v130
	v_lshl_add_u32 v128, v128, 3, s49
	v_lshlrev_b64 v[130:131], 12, v[130:131]
	v_ashrrev_i32_e32 v129, 31, v128
	v_lshl_add_u64 v[130:131], s[20:21], 0, v[130:131]
	v_lshl_add_u64 v[128:129], v[128:129], 1, v[130:131]
	global_load_dwordx4 v[164:167], v[128:129], off nt
	global_load_dwordx4 v[168:171], v[128:129], off offset:256 nt
	s_mov_b32 s99, 0
	s_mov_b32 s98, 0x10000
	v_lshl_add_u64 v[162:163], v[128:129], 0, s[98:99]
	global_load_dwordx4 v[172:175], v[162:163], off nt
	global_load_dwordx4 v[176:179], v[162:163], off offset:256 nt
	s_mov_b32 s98, 0x20000
	v_lshl_add_u64 v[162:163], v[128:129], 0, s[98:99]
	global_load_dwordx4 v[180:183], v[162:163], off nt
	global_load_dwordx4 v[184:187], v[162:163], off offset:256 nt
	s_mov_b32 s98, 0x30000
	v_lshl_add_u64 v[162:163], v[128:129], 0, s[98:99]
	global_load_dwordx4 v[188:191], v[162:163], off nt
	global_load_dwordx4 v[192:195], v[162:163], off offset:256 nt
	s_mov_b32 s98, 0x80000
	v_lshl_add_u64 v[162:163], v[128:129], 0, s[98:99]
	global_load_dwordx4 v[196:199], v[162:163], off nt
	global_load_dwordx4 v[200:203], v[162:163], off offset:256 nt
	s_mov_b32 s98, 0x90000
	v_lshl_add_u64 v[162:163], v[128:129], 0, s[98:99]
	global_load_dwordx4 v[204:207], v[162:163], off nt
	global_load_dwordx4 v[208:211], v[162:163], off offset:256 nt
	s_mov_b32 s98, 0xa0000
	v_lshl_add_u64 v[162:163], v[128:129], 0, s[98:99]
	global_load_dwordx4 v[218:221], v[162:163], off nt
	global_load_dwordx4 v[232:235], v[162:163], off offset:256 nt
	s_mov_b32 s98, 0xb0000
	v_lshl_add_u64 v[162:163], v[128:129], 0, s[98:99]
	global_load_dwordx4 v[236:239], v[162:163], off nt
	global_load_dwordx4 v[240:243], v[162:163], off offset:256 nt
.Lmid_early_skip:
	s_barrier
	s_add_i32 s94, s94, 2
	s_add_u32 s66, s66, 0x100
	s_addc_u32 s67, s67, 0
	s_cmp_gt_u32 s94, 13
	s_cbranch_scc1 .LBB0_625
; __device__ __forceinline__ float bflo(unsigned w) { return __uint_as_float(w << 16); }
; __device__ __forceinline__ float bfhi(unsigned w) { return __uint_as_float(w & 0xffff0000u); }
;     __device__ __forceinline__ void mid(f32x4 (&acc)[2][2][4][2], const Unit& u, int wr, int wc, int fr, int fq) const { scale(acc, u, wr, wc, fr, fq, 0); }
;     __device__ __forceinline__ void scale(f32x4 (&acc)[2][2][4][2], const Unit& u, int wr, int wc, int fr, int fq, int goff) const {
;         asm volatile("" : "+v"(fr), "+v"(fq));
;         const int row0 = u.pm * BM + wr * 64 + fr, col0 = u.pn * BM + wc * 32 + 8 * fq;
; #pragma unroll
;         for (int ai = 0; ai < 2; ++ai)
; #pragma unroll
;             for (int m = 0; m < 4; ++m) { const size_t row = (size_t)(row0 + ai * HALF + m * 16);
; #pragma unroll
;                 for (int bj = 0; bj < 2; ++bj) { const u32x4 g = __builtin_nontemporal_load((const u32x4*)(G + row * 2048 + goff + col0 + bj * HALF));
;                     f32x4& v0 = acc[ai][bj][m][0]; f32x4& v1 = acc[ai][bj][m][1];
;                     v0[0] *= bflo(g.x); v0[1] *= bfhi(g.x); v0[2] *= bflo(g.y); v0[3] *= bfhi(g.y); v1[0] *= bflo(g.z); v1[1] *= bfhi(g.z); v1[2] *= bflo(g.w); v1[3] *= bfhi(g.w); }
;                 if (m & 1) asm volatile("" ::: "memory"); }
; template <class Epi, class Sched, bool ALIGN_EPI = false, bool SP2 = false>
; __device__ __forceinline__ void gemm_phase(PG8_LAS unsigned char* lds, const Gemm g, const Sched& S, const Epi& E, const int wave_s) {
;     ...
;             if constexpr (Epi::MIDK > 0) { if (t == Epi::MIDK) E.mid(acc, cur, wr, wc, fr, fq); }
.LBB0_623:
	s_cmpk_lg_i32 s66, 0x400
	s_cbranch_scc1 .LBB0_622
	v_mov_b32_e32 v129, v152
	v_mov_b32_e32 v128, v153
	s_mov_b64 s[8:9], 0x10000
	v_add_u32_e32 v130, s51, v129
	v_ashrrev_i32_e32 v131, 31, v130
	v_lshl_add_u32 v128, v128, 3, s49
	v_lshlrev_b64 v[130:131], 12, v[130:131]
	v_ashrrev_i32_e32 v129, 31, v128
	v_lshl_add_u64 v[130:131], s[20:21], 0, v[130:131]
	v_lshl_add_u64 v[128:129], v[128:129], 1, v[130:131]
	s_waitcnt vmcnt(15)
	v_mov_b32_e32 v156, v164
	v_mov_b32_e32 v157, v165
	v_mov_b32_e32 v158, v166
	v_mov_b32_e32 v159, v167
	v_lshlrev_b32_e32 v130, 16, v156
	v_and_b32_e32 v131, 0xffff0000, v156
	v_pk_mul_f32 v[124:125], v[124:125], v[130:131]
	v_lshlrev_b32_e32 v130, 16, v157
	v_and_b32_e32 v131, 0xffff0000, v157
	v_pk_mul_f32 v[126:127], v[126:127], v[130:131]
	v_lshlrev_b32_e32 v130, 16, v158
	v_and_b32_e32 v131, 0xffff0000, v158
	v_pk_mul_f32 v[120:121], v[120:121], v[130:131]
	v_lshlrev_b32_e32 v130, 16, v159
	v_and_b32_e32 v131, 0xffff0000, v159
	v_pk_mul_f32 v[122:123], v[122:123], v[130:131]
	s_waitcnt vmcnt(14)
	v_mov_b32_e32 v156, v168
	v_mov_b32_e32 v157, v169
	v_mov_b32_e32 v158, v170
	v_mov_b32_e32 v159, v171
	v_lshlrev_b32_e32 v130, 16, v156
	v_and_b32_e32 v131, 0xffff0000, v156
	v_pk_mul_f32 v[116:117], v[116:117], v[130:131]
	v_lshlrev_b32_e32 v130, 16, v157
	v_and_b32_e32 v131, 0xffff0000, v157
	v_pk_mul_f32 v[118:119], v[118:119], v[130:131]
	v_lshlrev_b32_e32 v130, 16, v158
	v_and_b32_e32 v131, 0xffff0000, v158
	v_pk_mul_f32 v[112:113], v[112:113], v[130:131]
	v_lshlrev_b32_e32 v130, 16, v159
	v_and_b32_e32 v131, 0xffff0000, v159
	v_pk_mul_f32 v[114:115], v[114:115], v[130:131]
	v_lshl_add_u64 v[130:131], v[128:129], 0, s[8:9]
	s_mov_b32 s8, 0x10000
	v_add_co_u32_e32 v156, vcc, s8, v128
	s_mov_b64 s[8:9], 0x20000
	s_nop 0
	v_addc_co_u32_e32 v157, vcc, 0, v129, vcc
	s_waitcnt vmcnt(13)
	v_mov_b32_e32 v156, v172
	v_mov_b32_e32 v157, v173
	v_mov_b32_e32 v158, v174
	v_mov_b32_e32 v159, v175
	v_lshlrev_b32_e32 v160, 16, v156
	v_and_b32_e32 v161, 0xffff0000, v156
	v_lshlrev_b32_e32 v156, 16, v157
	v_and_b32_e32 v157, 0xffff0000, v157
	v_pk_mul_f32 v[110:111], v[110:111], v[156:157]
	v_lshlrev_b32_e32 v156, 16, v158
	v_and_b32_e32 v157, 0xffff0000, v158
	v_pk_mul_f32 v[104:105], v[104:105], v[156:157]
	v_lshlrev_b32_e32 v156, 16, v159
	v_and_b32_e32 v157, 0xffff0000, v159
	v_pk_mul_f32 v[106:107], v[106:107], v[156:157]
	v_pk_mul_f32 v[108:109], v[108:109], v[160:161]
	s_waitcnt vmcnt(12)
	v_mov_b32_e32 v156, v176
	v_mov_b32_e32 v157, v177
	v_mov_b32_e32 v158, v178
	v_mov_b32_e32 v159, v179
	v_lshlrev_b32_e32 v130, 16, v156
	v_and_b32_e32 v131, 0xffff0000, v156
	v_pk_mul_f32 v[100:101], v[100:101], v[130:131]
	v_lshlrev_b32_e32 v130, 16, v157
	v_and_b32_e32 v131, 0xffff0000, v157
	v_pk_mul_f32 v[102:103], v[102:103], v[130:131]
	v_lshlrev_b32_e32 v130, 16, v158
	v_and_b32_e32 v131, 0xffff0000, v158
	v_pk_mul_f32 v[96:97], v[96:97], v[130:131]
	v_lshlrev_b32_e32 v130, 16, v159
	v_and_b32_e32 v131, 0xffff0000, v159
	v_pk_mul_f32 v[98:99], v[98:99], v[130:131]
	v_lshl_add_u64 v[130:131], v[128:129], 0, s[8:9]
	s_mov_b32 s8, 0x20000
	v_add_co_u32_e32 v156, vcc, s8, v128
	s_nop 1
	v_addc_co_u32_e32 v157, vcc, 0, v129, vcc
	s_waitcnt vmcnt(11)
	v_mov_b32_e32 v156, v180
	v_mov_b32_e32 v157, v181
	v_mov_b32_e32 v158, v182
	v_mov_b32_e32 v159, v183
	v_lshlrev_b32_e32 v160, 16, v156
	v_and_b32_e32 v161, 0xffff0000, v156
	v_lshlrev_b32_e32 v156, 16, v157
	v_and_b32_e32 v157, 0xffff0000, v157
	v_pk_mul_f32 v[94:95], v[94:95], v[156:157]
	v_lshlrev_b32_e32 v156, 16, v158
	v_and_b32_e32 v157, 0xffff0000, v158
	v_pk_mul_f32 v[88:89], v[88:89], v[156:157]
	v_lshlrev_b32_e32 v156, 16, v159
	v_and_b32_e32 v157, 0xffff0000, v159
	v_pk_mul_f32 v[90:91], v[90:91], v[156:157]
	v_pk_mul_f32 v[92:93], v[92:93], v[160:161]
	s_waitcnt vmcnt(10)
	v_mov_b32_e32 v156, v184
	v_mov_b32_e32 v157, v185
	v_mov_b32_e32 v158, v186
	v_mov_b32_e32 v159, v187
	v_lshlrev_b32_e32 v130, 16, v156
	v_and_b32_e32 v131, 0xffff0000, v156
	v_pk_mul_f32 v[84:85], v[84:85], v[130:131]
	v_lshlrev_b32_e32 v130, 16, v157
	v_and_b32_e32 v131, 0xffff0000, v157
	v_add_co_u32_e32 v156, vcc, s13, v128
	v_pk_mul_f32 v[86:87], v[86:87], v[130:131]
	v_lshlrev_b32_e32 v130, 16, v158
	v_and_b32_e32 v131, 0xffff0000, v158
	v_addc_co_u32_e32 v157, vcc, 0, v129, vcc
	v_pk_mul_f32 v[80:81], v[80:81], v[130:131]
	v_lshlrev_b32_e32 v130, 16, v159
	v_and_b32_e32 v131, 0xffff0000, v159
	v_pk_mul_f32 v[82:83], v[82:83], v[130:131]
	v_lshl_add_u64 v[130:131], v[128:129], 0, s[38:39]
	s_waitcnt vmcnt(9)
	v_mov_b32_e32 v156, v188
	v_mov_b32_e32 v157, v189
	v_mov_b32_e32 v158, v190
	v_mov_b32_e32 v159, v191
	v_lshlrev_b32_e32 v160, 16, v156
	v_and_b32_e32 v161, 0xffff0000, v156
	v_lshlrev_b32_e32 v156, 16, v157
	v_and_b32_e32 v157, 0xffff0000, v157
	v_pk_mul_f32 v[78:79], v[78:79], v[156:157]
	v_lshlrev_b32_e32 v156, 16, v158
	v_and_b32_e32 v157, 0xffff0000, v158
	v_pk_mul_f32 v[72:73], v[72:73], v[156:157]
	v_lshlrev_b32_e32 v156, 16, v159
	v_and_b32_e32 v157, 0xffff0000, v159
	v_pk_mul_f32 v[74:75], v[74:75], v[156:157]
	v_pk_mul_f32 v[76:77], v[76:77], v[160:161]
	s_waitcnt vmcnt(8)
; __device__ __forceinline__ float bflo(unsigned w) { return __uint_as_float(w << 16); }
; __device__ __forceinline__ float bfhi(unsigned w) { return __uint_as_float(w & 0xffff0000u); }
;     __device__ __forceinline__ void scale(f32x4 (&acc)[2][2][4][2], const Unit& u, int wr, int wc, int fr, int fq, int goff) const {
;     ...
;             for (int m = 0; m < 4; ++m) { const size_t row = (size_t)(row0 + ai * HALF + m * 16);
; #pragma unroll
;                 for (int bj = 0; bj < 2; ++bj) { const u32x4 g = __builtin_nontemporal_load((const u32x4*)(G + row * 2048 + goff + col0 + bj * HALF));
;                     f32x4& v0 = acc[ai][bj][m][0]; f32x4& v1 = acc[ai][bj][m][1];
;                     v0[0] *= bflo(g.x); v0[1] *= bfhi(g.x); v0[2] *= bflo(g.y); v0[3] *= bfhi(g.y); v1[0] *= bflo(g.z); v1[1] *= bfhi(g.z); v1[2] *= bflo(g.w); v1[3] *= bfhi(g.w); }
;                 if (m & 1) asm volatile("" ::: "memory"); }
	v_mov_b32_e32 v156, v192
	v_mov_b32_e32 v157, v193
	v_mov_b32_e32 v158, v194
	v_mov_b32_e32 v159, v195
	v_lshlrev_b32_e32 v130, 16, v156
	v_and_b32_e32 v131, 0xffff0000, v156
	v_pk_mul_f32 v[68:69], v[68:69], v[130:131]
	v_lshlrev_b32_e32 v130, 16, v157
	v_and_b32_e32 v131, 0xffff0000, v157
	v_add_co_u32_e32 v156, vcc, s83, v128
	v_pk_mul_f32 v[70:71], v[70:71], v[130:131]
	v_lshlrev_b32_e32 v130, 16, v158
	v_and_b32_e32 v131, 0xffff0000, v158
	v_addc_co_u32_e32 v157, vcc, 0, v129, vcc
	v_pk_mul_f32 v[64:65], v[64:65], v[130:131]
	v_lshlrev_b32_e32 v130, 16, v159
	v_and_b32_e32 v131, 0xffff0000, v159
	v_pk_mul_f32 v[66:67], v[66:67], v[130:131]
	v_lshl_add_u64 v[130:131], v[128:129], 0, s[40:41]
	s_waitcnt vmcnt(7)
	v_mov_b32_e32 v156, v196
	v_mov_b32_e32 v157, v197
	v_mov_b32_e32 v158, v198
	v_mov_b32_e32 v159, v199
	v_lshlrev_b32_e32 v160, 16, v156
	v_and_b32_e32 v161, 0xffff0000, v156
	v_lshlrev_b32_e32 v156, 16, v157
	v_and_b32_e32 v157, 0xffff0000, v157
	v_pk_mul_f32 v[62:63], v[62:63], v[156:157]
	v_lshlrev_b32_e32 v156, 16, v158
	v_and_b32_e32 v157, 0xffff0000, v158
	v_pk_mul_f32 v[56:57], v[56:57], v[156:157]
	v_lshlrev_b32_e32 v156, 16, v159
	v_and_b32_e32 v157, 0xffff0000, v159
	v_pk_mul_f32 v[58:59], v[58:59], v[156:157]
	v_pk_mul_f32 v[60:61], v[60:61], v[160:161]
	s_waitcnt vmcnt(6)
	v_mov_b32_e32 v156, v200
	v_mov_b32_e32 v157, v201
	v_mov_b32_e32 v158, v202
	v_mov_b32_e32 v159, v203
	v_lshlrev_b32_e32 v130, 16, v156
	v_and_b32_e32 v131, 0xffff0000, v156
	v_pk_mul_f32 v[52:53], v[52:53], v[130:131]
	v_lshlrev_b32_e32 v130, 16, v157
	v_and_b32_e32 v131, 0xffff0000, v157
	v_add_co_u32_e32 v156, vcc, s86, v128
	v_pk_mul_f32 v[54:55], v[54:55], v[130:131]
	v_lshlrev_b32_e32 v130, 16, v158
	v_and_b32_e32 v131, 0xffff0000, v158
	v_addc_co_u32_e32 v157, vcc, 0, v129, vcc
	v_pk_mul_f32 v[48:49], v[48:49], v[130:131]
	v_lshlrev_b32_e32 v130, 16, v159
	v_and_b32_e32 v131, 0xffff0000, v159
	v_pk_mul_f32 v[50:51], v[50:51], v[130:131]
	v_lshl_add_u64 v[130:131], v[128:129], 0, s[42:43]
	s_waitcnt vmcnt(5)
	v_mov_b32_e32 v156, v204
	v_mov_b32_e32 v157, v205
	v_mov_b32_e32 v158, v206
	v_mov_b32_e32 v159, v207
	v_lshlrev_b32_e32 v160, 16, v156
	v_and_b32_e32 v161, 0xffff0000, v156
	v_lshlrev_b32_e32 v156, 16, v157
	v_and_b32_e32 v157, 0xffff0000, v157
	v_pk_mul_f32 v[46:47], v[46:47], v[156:157]
	v_lshlrev_b32_e32 v156, 16, v158
	v_and_b32_e32 v157, 0xffff0000, v158
	v_pk_mul_f32 v[40:41], v[40:41], v[156:157]
	v_lshlrev_b32_e32 v156, 16, v159
	v_and_b32_e32 v157, 0xffff0000, v159
	v_pk_mul_f32 v[42:43], v[42:43], v[156:157]
	v_pk_mul_f32 v[44:45], v[44:45], v[160:161]
	s_waitcnt vmcnt(4)
	v_mov_b32_e32 v156, v208
	v_mov_b32_e32 v157, v209
	v_mov_b32_e32 v158, v210
	v_mov_b32_e32 v159, v211
	v_lshlrev_b32_e32 v130, 16, v156
	v_and_b32_e32 v131, 0xffff0000, v156
	v_pk_mul_f32 v[36:37], v[36:37], v[130:131]
	v_lshlrev_b32_e32 v130, 16, v157
	v_and_b32_e32 v131, 0xffff0000, v157
	v_add_co_u32_e32 v156, vcc, s87, v128
	v_pk_mul_f32 v[38:39], v[38:39], v[130:131]
	v_lshlrev_b32_e32 v130, 16, v158
	v_and_b32_e32 v131, 0xffff0000, v158
	v_addc_co_u32_e32 v157, vcc, 0, v129, vcc
	v_pk_mul_f32 v[32:33], v[32:33], v[130:131]
	v_lshlrev_b32_e32 v130, 16, v159
	v_and_b32_e32 v131, 0xffff0000, v159
	v_pk_mul_f32 v[34:35], v[34:35], v[130:131]
	v_lshl_add_u64 v[130:131], v[128:129], 0, s[44:45]
	s_waitcnt vmcnt(3)
	v_mov_b32_e32 v156, v218
	v_mov_b32_e32 v157, v219
	v_mov_b32_e32 v158, v220
	v_mov_b32_e32 v159, v221
	v_lshlrev_b32_e32 v160, 16, v156
	v_and_b32_e32 v161, 0xffff0000, v156
	v_lshlrev_b32_e32 v156, 16, v157
	v_and_b32_e32 v157, 0xffff0000, v157
	v_pk_mul_f32 v[30:31], v[30:31], v[156:157]
	v_lshlrev_b32_e32 v156, 16, v158
	v_and_b32_e32 v157, 0xffff0000, v158
	v_pk_mul_f32 v[24:25], v[24:25], v[156:157]
	v_lshlrev_b32_e32 v156, 16, v159
	v_and_b32_e32 v157, 0xffff0000, v159
	v_pk_mul_f32 v[26:27], v[26:27], v[156:157]
	v_pk_mul_f32 v[28:29], v[28:29], v[160:161]
	s_waitcnt vmcnt(2)
	v_mov_b32_e32 v156, v232
	v_mov_b32_e32 v157, v233
	v_mov_b32_e32 v158, v234
	v_mov_b32_e32 v159, v235
	v_lshlrev_b32_e32 v130, 16, v156
	v_and_b32_e32 v131, 0xffff0000, v156
	v_pk_mul_f32 v[20:21], v[20:21], v[130:131]
	v_lshlrev_b32_e32 v130, 16, v157
	v_and_b32_e32 v131, 0xffff0000, v157
	v_pk_mul_f32 v[22:23], v[22:23], v[130:131]
	v_lshlrev_b32_e32 v130, 16, v158
	v_and_b32_e32 v131, 0xffff0000, v158
	v_lshl_add_u64 v[156:157], v[128:129], 0, s[46:47]
	v_add_co_u32_e32 v128, vcc, s88, v128
	v_pk_mul_f32 v[16:17], v[16:17], v[130:131]
	v_lshlrev_b32_e32 v130, 16, v159
	v_and_b32_e32 v131, 0xffff0000, v159
	v_addc_co_u32_e32 v129, vcc, 0, v129, vcc
	v_pk_mul_f32 v[18:19], v[18:19], v[130:131]
	s_waitcnt vmcnt(1)
	v_mov_b32_e32 v128, v236
	v_mov_b32_e32 v129, v237
	v_mov_b32_e32 v130, v238
	v_mov_b32_e32 v131, v239
	v_lshlrev_b32_e32 v158, 16, v128
	v_and_b32_e32 v159, 0xffff0000, v128
	v_lshlrev_b32_e32 v128, 16, v129
	v_and_b32_e32 v129, 0xffff0000, v129
	v_pk_mul_f32 v[14:15], v[14:15], v[128:129]
	v_lshlrev_b32_e32 v128, 16, v130
	v_and_b32_e32 v129, 0xffff0000, v130
	v_pk_mul_f32 v[8:9], v[8:9], v[128:129]
	v_lshlrev_b32_e32 v128, 16, v131
	v_and_b32_e32 v129, 0xffff0000, v131
	v_pk_mul_f32 v[10:11], v[10:11], v[128:129]
	v_pk_mul_f32 v[12:13], v[12:13], v[158:159]
	s_waitcnt vmcnt(0)
	v_mov_b32_e32 v128, v240
	v_mov_b32_e32 v129, v241
	v_mov_b32_e32 v130, v242
	v_mov_b32_e32 v131, v243
	v_lshlrev_b32_e32 v156, 16, v128
	v_and_b32_e32 v157, 0xffff0000, v128
	v_lshlrev_b32_e32 v128, 16, v129
	v_and_b32_e32 v129, 0xffff0000, v129
	v_pk_mul_f32 v[6:7], v[6:7], v[128:129]
	v_lshlrev_b32_e32 v128, 16, v130
	v_and_b32_e32 v129, 0xffff0000, v130
	v_pk_mul_f32 v[0:1], v[0:1], v[128:129]
	v_lshlrev_b32_e32 v128, 16, v131
	v_and_b32_e32 v129, 0xffff0000, v131
	v_pk_mul_f32 v[4:5], v[4:5], v[156:157]
	v_pk_mul_f32 v[2:3], v[2:3], v[128:129]
	s_branch .LBB0_622
